# read-once residual loads of the Wout / FF2 epilogues non-temporal
# speedup vs baseline: 1.0057x; 1.0057x over previous
;     __device__ __forceinline__ void operator()(const f32x4 (&acc)[2][2][4][2], const pg8::Unit& u, int wr, int wc, int fr, int fq) const {
;         u32x4 xr[2][4][2];
; #pragma unroll
;         for (int ai = 0; ai < 2; ++ai)
; #pragma unroll
;             for (int m = 0; m < 4; ++m)
; #pragma unroll
;                 for (int bj = 0; bj < 2; ++bj)
;                     xr[ai][m][bj] = *(const u32x4*)(xb + (size_t)(u.pm * 256 + ai * 128 + wr * 64 + m * 16 + fr) * DM + u.pn * 256 + 128 * bj + 32 * wc + 8 * fq);
;         __builtin_amdgcn_sched_barrier(0);
; #pragma unroll
;         for (int ai = 0; ai < 2; ++ai)
; #pragma unroll
;             for (int m = 0; m < 4; ++m) {
;                 const int row = u.pm * 256 + ai * 128 + wr * 64 + m * 16 + fr;
;                 float ss = 0.f;
; #pragma unroll
;                 for (int bj = 0; bj < 2; ++bj) {
;                     const size_t off = (size_t)row * DM + u.pn * 256 + 128 * bj + 32 * wc + 8 * fq;
;                     const u32x4 w = xr[ai][m][bj];
;                     float y[8];
;                     y[0] = __uint_as_float(w.x << 16) + acc[ai][bj][m][0].x; y[1] = __uint_as_float(w.x & 0xffff0000u) + acc[ai][bj][m][0].y;
;                     y[2] = __uint_as_float(w.y << 16) + acc[ai][bj][m][0].z; y[3] = __uint_as_float(w.y & 0xffff0000u) + acc[ai][bj][m][0].w;
;                     y[4] = __uint_as_float(w.z << 16) + acc[ai][bj][m][1].x; y[5] = __uint_as_float(w.z & 0xffff0000u) + acc[ai][bj][m][1].y;
;                     y[6] = __uint_as_float(w.w << 16) + acc[ai][bj][m][1].z; y[7] = __uint_as_float(w.w & 0xffff0000u) + acc[ai][bj][m][1].w;
;                     store8(x2b + off, y);
; #pragma unroll
;                     for (int i = 0; i < 8; ++i) ss += y[i] * y[i];
;                 }
;                 ss += __shfl_xor(ss, 16); ss += __shfl_xor(ss, 32);
;                 if (fq == 0) red[wc * 256 + (row & 255)] = ss;
.Lx_ok:
	s_lshl_b32 s9, s34, 8
	s_lshl_b32 s34, s8, 8
	v_add_u32_e32 v120, s9, v185
	s_ashr_i32 s35, s34, 31
	s_lshl_b64 s[36:37], s[34:35], 1
	v_ashrrev_i32_e32 v121, 31, v120
	v_or_b32_e32 v230, 16, v120
	v_lshl_add_u64 v[122:123], v[196:197], 0, s[36:37]
	v_lshlrev_b64 v[250:251], 11, v[120:121]
	v_ashrrev_i32_e32 v231, 31, v230
	v_or_b32_e32 v226, 32, v120
	v_lshl_add_u64 v[124:125], v[122:123], 0, v[250:251]
	v_lshlrev_b64 v[232:233], 11, v[230:231]
	v_ashrrev_i32_e32 v227, 31, v226
	v_or_b32_e32 v222, 48, v120
	global_load_dwordx4 v[242:245], v[124:125], off nt
	global_load_dwordx4 v[246:249], v[124:125], off offset:256 nt
	v_lshl_add_u64 v[124:125], v[122:123], 0, v[232:233]
	v_lshlrev_b64 v[228:229], 11, v[226:227]
	v_ashrrev_i32_e32 v223, 31, v222
	v_add_u32_e32 v218, 0x80, v120
	global_load_dwordx4 v[180:183], v[124:125], off nt
	global_load_dwordx4 v[176:179], v[124:125], off offset:256 nt
	v_lshl_add_u64 v[124:125], v[122:123], 0, v[228:229]
	v_lshlrev_b64 v[224:225], 11, v[222:223]
	v_ashrrev_i32_e32 v219, 31, v218
	v_add_u32_e32 v214, 0x90, v120
	global_load_dwordx4 v[172:175], v[124:125], off nt
	global_load_dwordx4 v[168:171], v[124:125], off offset:256 nt
	v_lshl_add_u64 v[124:125], v[122:123], 0, v[224:225]
	v_lshlrev_b64 v[220:221], 11, v[218:219]
	v_ashrrev_i32_e32 v215, 31, v214
	v_add_u32_e32 v210, 0xa0, v120
	v_add_u32_e32 v206, 0xb0, v120
	global_load_dwordx4 v[164:167], v[124:125], off nt
	global_load_dwordx4 v[160:163], v[124:125], off offset:256 nt
	v_lshl_add_u64 v[124:125], v[122:123], 0, v[220:221]
	v_lshlrev_b64 v[216:217], 11, v[214:215]
	v_ashrrev_i32_e32 v211, 31, v210
	v_ashrrev_i32_e32 v207, 31, v206
	global_load_dwordx4 v[156:159], v[124:125], off nt
	global_load_dwordx4 v[152:155], v[124:125], off offset:256 nt
	v_lshl_add_u64 v[124:125], v[122:123], 0, v[216:217]
	v_lshlrev_b64 v[212:213], 11, v[210:211]
	v_lshlrev_b64 v[208:209], 11, v[206:207]
	global_load_dwordx4 v[148:151], v[124:125], off nt
	global_load_dwordx4 v[144:147], v[124:125], off offset:256 nt
	v_lshl_add_u64 v[124:125], v[122:123], 0, v[212:213]
	v_lshl_add_u64 v[120:121], v[122:123], 0, v[208:209]
	global_load_dwordx4 v[140:143], v[124:125], off nt
	global_load_dwordx4 v[136:139], v[124:125], off offset:256 nt
	s_nop 0
	global_load_dwordx4 v[124:127], v[120:121], off nt
	s_nop 0
	global_load_dwordx4 v[120:123], v[120:121], off offset:256 nt
	s_waitcnt vmcnt(0)
	v_lshlrev_b32_e32 v207, 16, v242
	v_add_f32_e32 v207, v132, v207
	v_and_b32_e32 v132, 0xffff0000, v242
	v_add_f32_e32 v211, v133, v132
	v_lshlrev_b32_e32 v132, 16, v243
	v_add_f32_e32 v134, v134, v132
	v_and_b32_e32 v132, 0xffff0000, v243
	v_add_f32_e32 v135, v135, v132
	v_lshlrev_b32_e32 v132, 16, v244
	v_add_f32_e32 v215, v128, v132
	v_and_b32_e32 v128, 0xffff0000, v244
	v_add_f32_e32 v219, v129, v128
	v_lshlrev_b32_e32 v128, 16, v245
	v_add_f32_e32 v223, v130, v128
	v_and_b32_e32 v128, 0xffff0000, v245
	v_add_f32_e32 v131, v131, v128
	v_lshl_add_u64 v[128:129], s[16:17], 0, v[250:251]
	v_lshl_add_u64 v[128:129], v[128:129], 0, s[36:37]
	v_lshl_add_u64 v[128:129], v[128:129], 0, s[10:11]
	v_lshl_add_u64 v[132:133], v[128:129], 0, v[194:195]
	v_cvt_pk_bf16_f32 v128, v207, v211
	v_mul_f32_e32 v211, v211, v211
	v_fmac_f32_e32 v211, v207, v207
	v_fmac_f32_e32 v211, v134, v134
	v_fmac_f32_e32 v211, v135, v135
	v_fmac_f32_e32 v211, v215, v215
	v_lshlrev_b32_e32 v130, 16, v246
	v_fmac_f32_e32 v211, v219, v219
	v_add_f32_e32 v116, v116, v130
	v_and_b32_e32 v130, 0xffff0000, v246
	v_fmac_f32_e32 v211, v223, v223
	v_add_f32_e32 v117, v117, v130
	v_lshlrev_b32_e32 v130, 16, v247
	v_fmac_f32_e32 v211, v131, v131
	v_add_f32_e32 v118, v118, v130
	v_and_b32_e32 v130, 0xffff0000, v247
	v_add_f32_e32 v119, v119, v130
	v_lshlrev_b32_e32 v130, 16, v248
	v_fmac_f32_e32 v211, v116, v116
	v_cvt_pk_bf16_f32 v129, v134, v135
	v_add_f32_e32 v134, v112, v130
	v_and_b32_e32 v112, 0xffff0000, v248
	v_fmac_f32_e32 v211, v117, v117
	v_add_f32_e32 v135, v113, v112
	v_lshlrev_b32_e32 v112, 16, v249
	v_fmac_f32_e32 v211, v118, v118
	v_add_f32_e32 v207, v114, v112
	v_and_b32_e32 v112, 0xffff0000, v249
	v_fmac_f32_e32 v211, v119, v119
	v_and_b32_e32 v113, 64, v240
	v_add_f32_e32 v227, v115, v112
	v_fmac_f32_e32 v211, v134, v134
	v_xor_b32_e32 v112, 16, v240
	v_add_u32_e32 v113, 64, v113
	v_fmac_f32_e32 v211, v135, v135
	v_cmp_lt_i32_e32 vcc, v112, v113
	v_fmac_f32_e32 v211, v207, v207
	v_fmac_f32_e32 v211, v227, v227
	v_cndmask_b32_e32 v112, v240, v112, vcc
	v_lshlrev_b32_e32 v112, 2, v112
	ds_bpermute_b32 v114, v112, v211
	v_xor_b32_e32 v115, 32, v240
	v_cmp_lt_i32_e32 vcc, v115, v113
	v_cvt_pk_bf16_f32 v130, v215, v219
	v_cvt_pk_bf16_f32 v131, v223, v131
	s_waitcnt lgkmcnt(0)
	v_add_f32_e32 v114, v211, v114
	global_store_dwordx4 v[132:133], v[128:131], off
	v_cndmask_b32_e32 v113, v240, v115, vcc
	v_lshlrev_b32_e32 v113, 2, v113
	ds_bpermute_b32 v115, v113, v114
	v_cvt_pk_bf16_f32 v116, v116, v117
	v_cvt_pk_bf16_f32 v117, v118, v119
	v_cvt_pk_bf16_f32 v118, v134, v135
	v_cvt_pk_bf16_f32 v119, v207, v227
	global_store_dwordx4 v[132:133], v[116:119], off offset:256
	s_and_saveexec_b64 s[36:37], s[2:3]
	s_cbranch_execz .LBB0_940
	s_waitcnt lgkmcnt(0)
	v_add_f32_e32 v114, v114, v115
	ds_write_b32 v235, v114

;     __device__ __forceinline__ void operator()(const f32x4 (&acc)[2][2][4][2], const pg8::Unit& u, int wr, int wc, int fr, int fq) const {
;         u32x4 xr[2][4][2];
; #pragma unroll
;         for (int ai = 0; ai < 2; ++ai)
; #pragma unroll
;             for (int m = 0; m < 4; ++m)
; #pragma unroll
;                 for (int bj = 0; bj < 2; ++bj)
;                     xr[ai][m][bj] = *(const u32x4*)(x2b + (size_t)(u.pm * 256 + ai * 128 + wr * 64 + m * 16 + fr) * DM + u.pn * 256 + 128 * bj + 32 * wc + 8 * fq);
;         __builtin_amdgcn_sched_barrier(0);
; #pragma unroll
;         for (int ai = 0; ai < 2; ++ai)
; #pragma unroll
;             for (int m = 0; m < 4; ++m) {
;                 const int row = u.pm * 256 + ai * 128 + wr * 64 + m * 16 + fr;
; #pragma unroll
;                 for (int bj = 0; bj < 2; ++bj) {
;                     const size_t off = (size_t)row * DM + u.pn * 256 + 128 * bj + 32 * wc + 8 * fq;
;                     const u32x4 w = xr[ai][m][bj];
;                     f32x4 ya = acc[ai][bj][m][0], yb = acc[ai][bj][m][1];
;                     ya.x += __uint_as_float(w.x << 16); ya.y += __uint_as_float(w.x & 0xffff0000u); ya.z += __uint_as_float(w.y << 16); ya.w += __uint_as_float(w.y & 0xffff0000u);
;                     yb.x += __uint_as_float(w.z << 16); yb.y += __uint_as_float(w.z & 0xffff0000u); yb.z += __uint_as_float(w.w << 16); yb.w += __uint_as_float(w.w & 0xffff0000u);
;                     *(f32x4*)(out + off) = ya; *(f32x4*)(out + off + 4) = yb;
.LBB0_1064:
	v_lshl_add_u32 v226, s16, 8, v179
	s_lshl_b32 s18, s40, 8
	s_ashr_i32 s19, s18, 31
	v_ashrrev_i32_e32 v227, 31, v226
	v_lshl_add_u64 v[128:129], s[18:19], 1, v[176:177]
	v_lshlrev_b64 v[130:131], 11, v[226:227]
	v_or_b32_e32 v228, 16, v226
	v_lshl_add_u64 v[130:131], v[128:129], 0, v[130:131]
	v_ashrrev_i32_e32 v229, 31, v228
	global_load_dwordx4 v[202:205], v[130:131], off nt
	global_load_dwordx4 v[206:209], v[130:131], off offset:256 nt
	v_lshlrev_b64 v[130:131], 11, v[228:229]
	v_or_b32_e32 v230, 32, v226
	v_lshl_add_u64 v[130:131], v[128:129], 0, v[130:131]
	v_ashrrev_i32_e32 v231, 31, v230
	global_load_dwordx4 v[210:213], v[130:131], off nt
	global_load_dwordx4 v[214:217], v[130:131], off offset:256 nt
	v_lshlrev_b64 v[130:131], 11, v[230:231]
	v_or_b32_e32 v196, 48, v226
	v_lshl_add_u64 v[130:131], v[128:129], 0, v[130:131]
	v_ashrrev_i32_e32 v197, 31, v196
	global_load_dwordx4 v[218:221], v[130:131], off nt
	global_load_dwordx4 v[222:225], v[130:131], off offset:256 nt
	v_lshlrev_b64 v[130:131], 11, v[196:197]
	v_add_u32_e32 v194, 0x80, v226
	v_lshl_add_u64 v[130:131], v[128:129], 0, v[130:131]
	v_ashrrev_i32_e32 v195, 31, v194
	global_load_dwordx4 v[164:167], v[130:131], off nt
	global_load_dwordx4 v[160:163], v[130:131], off offset:256 nt
	v_lshlrev_b64 v[130:131], 11, v[194:195]
	v_add_u32_e32 v192, 0x90, v226
	v_lshl_add_u64 v[130:131], v[128:129], 0, v[130:131]
	v_ashrrev_i32_e32 v193, 31, v192
	global_load_dwordx4 v[156:159], v[130:131], off nt
	global_load_dwordx4 v[152:155], v[130:131], off offset:256 nt
	v_lshlrev_b64 v[130:131], 11, v[192:193]
	v_add_u32_e32 v190, 0xa0, v226
	v_lshl_add_u64 v[130:131], v[128:129], 0, v[130:131]
	v_ashrrev_i32_e32 v191, 31, v190
	global_load_dwordx4 v[148:151], v[130:131], off nt
	global_load_dwordx4 v[144:147], v[130:131], off offset:256 nt
	v_lshlrev_b64 v[130:131], 11, v[190:191]
	v_add_u32_e32 v188, 0xb0, v226
	v_lshl_add_u64 v[130:131], v[128:129], 0, v[130:131]
	v_ashrrev_i32_e32 v189, 31, v188
	global_load_dwordx4 v[140:143], v[130:131], off nt
	global_load_dwordx4 v[136:139], v[130:131], off offset:256 nt
	v_lshlrev_b64 v[130:131], 11, v[188:189]
	v_lshl_add_u64 v[128:129], v[128:129], 0, v[130:131]
	global_load_dwordx4 v[132:135], v[128:129], off nt
	s_nop 0
	global_load_dwordx4 v[128:131], v[128:129], off offset:256 nt
	s_waitcnt vmcnt(0)
	v_lshlrev_b32_e32 v234, 16, v202
	v_and_b32_e32 v235, 0xffff0000, v202
	v_lshlrev_b32_e32 v202, 16, v203
	v_and_b32_e32 v203, 0xffff0000, v203
	v_pk_add_f32 v[126:127], v[126:127], v[202:203]
	v_lshlrev_b32_e32 v202, 16, v204
	v_and_b32_e32 v203, 0xffff0000, v204
	v_pk_add_f32 v[202:203], v[120:121], v[202:203]
	v_lshlrev_b32_e32 v120, 16, v205
	v_and_b32_e32 v121, 0xffff0000, v205
	v_mov_b32_e32 v233, s19
	v_or_b32_e32 v232, s18, v178
	v_pk_add_f32 v[204:205], v[122:123], v[120:121]
	v_lshlrev_b64 v[120:121], 12, v[226:227]
	v_lshl_add_u64 v[122:123], s[76:77], 0, v[120:121]
	v_lshlrev_b64 v[120:121], 2, v[232:233]
	v_pk_add_f32 v[124:125], v[124:125], v[234:235]
	v_lshl_add_u64 v[122:123], v[122:123], 0, v[120:121]
	global_store_dwordx4 v[122:123], v[124:127], off nt
	global_store_dwordx4 v[122:123], v[202:205], off offset:16 nt
	s_andn2_b64 vcc, exec, s[0:1]
	v_lshlrev_b32_e32 v124, 16, v206
	v_and_b32_e32 v125, 0xffff0000, v206
	v_pk_add_f32 v[116:117], v[116:117], v[124:125]
	v_lshlrev_b32_e32 v124, 16, v207
	v_and_b32_e32 v125, 0xffff0000, v207
	v_pk_add_f32 v[118:119], v[118:119], v[124:125]
	v_lshlrev_b32_e32 v124, 16, v208
	v_and_b32_e32 v125, 0xffff0000, v208
	v_pk_add_f32 v[108:109], v[108:109], v[124:125]
	v_lshlrev_b32_e32 v124, 16, v209
	v_and_b32_e32 v125, 0xffff0000, v209
	v_pk_add_f32 v[110:111], v[110:111], v[124:125]
	global_store_dwordx4 v[122:123], v[116:119], off offset:512 nt
	global_store_dwordx4 v[122:123], v[108:111], off offset:528 nt
	s_mov_b64 s[0:1], -1
	s_nop 0
	v_lshlrev_b32_e32 v108, 16, v210
	v_and_b32_e32 v109, 0xffff0000, v210
	v_pk_add_f32 v[108:109], v[112:113], v[108:109]
	v_lshlrev_b32_e32 v112, 16, v212
	v_and_b32_e32 v113, 0xffff0000, v212
	v_pk_add_f32 v[104:105], v[104:105], v[112:113]
	v_lshlrev_b32_e32 v112, 16, v213
	v_and_b32_e32 v113, 0xffff0000, v213
	v_pk_add_f32 v[106:107], v[106:107], v[112:113]
	v_lshlrev_b64 v[112:113], 12, v[228:229]
	v_lshlrev_b32_e32 v110, 16, v211
	v_and_b32_e32 v111, 0xffff0000, v211
	v_lshl_add_u64 v[112:113], s[76:77], 0, v[112:113]
	v_pk_add_f32 v[110:111], v[114:115], v[110:111]
	v_lshl_add_u64 v[112:113], v[112:113], 0, v[120:121]
	global_store_dwordx4 v[112:113], v[108:111], off nt
	global_store_dwordx4 v[112:113], v[104:107], off offset:16 nt
	s_nop 1
	v_lshlrev_b32_e32 v104, 16, v214
	v_and_b32_e32 v105, 0xffff0000, v214
	v_pk_add_f32 v[100:101], v[100:101], v[104:105]
	v_lshlrev_b32_e32 v104, 16, v215
	v_and_b32_e32 v105, 0xffff0000, v215
	v_pk_add_f32 v[102:103], v[102:103], v[104:105]
	v_lshlrev_b32_e32 v104, 16, v216
	v_and_b32_e32 v105, 0xffff0000, v216
	v_pk_add_f32 v[92:93], v[92:93], v[104:105]
	v_lshlrev_b32_e32 v104, 16, v217
	v_and_b32_e32 v105, 0xffff0000, v217
	v_pk_add_f32 v[94:95], v[94:95], v[104:105]
	global_store_dwordx4 v[112:113], v[100:103], off offset:512 nt
	global_store_dwordx4 v[112:113], v[92:95], off offset:528 nt
	s_nop 1
	v_lshlrev_b32_e32 v92, 16, v218
	v_and_b32_e32 v93, 0xffff0000, v218
	v_pk_add_f32 v[92:93], v[96:97], v[92:93]
	v_lshlrev_b32_e32 v96, 16, v220
	v_and_b32_e32 v97, 0xffff0000, v220
	v_pk_add_f32 v[88:89], v[88:89], v[96:97]
	v_lshlrev_b32_e32 v96, 16, v221
	v_and_b32_e32 v97, 0xffff0000, v221
	v_pk_add_f32 v[90:91], v[90:91], v[96:97]
	v_lshlrev_b64 v[96:97], 12, v[230:231]
	v_lshlrev_b32_e32 v94, 16, v219
;     __device__ __forceinline__ void operator()(const f32x4 (&acc)[2][2][4][2], const pg8::Unit& u, int wr, int wc, int fr, int fq) const {
;     ...
;                 for (int bj = 0; bj < 2; ++bj) {
;                     const size_t off = (size_t)row * DM + u.pn * 256 + 128 * bj + 32 * wc + 8 * fq;
;                     const u32x4 w = xr[ai][m][bj];
;                     f32x4 ya = acc[ai][bj][m][0], yb = acc[ai][bj][m][1];
;                     ya.x += __uint_as_float(w.x << 16); ya.y += __uint_as_float(w.x & 0xffff0000u); ya.z += __uint_as_float(w.y << 16); ya.w += __uint_as_float(w.y & 0xffff0000u);
;                     yb.x += __uint_as_float(w.z << 16); yb.y += __uint_as_float(w.z & 0xffff0000u); yb.z += __uint_as_float(w.w << 16); yb.w += __uint_as_float(w.w & 0xffff0000u);
;                     *(f32x4*)(out + off) = ya; *(f32x4*)(out + off + 4) = yb;
;                 }
;             }
	v_and_b32_e32 v95, 0xffff0000, v219
	v_lshl_add_u64 v[96:97], s[76:77], 0, v[96:97]
	v_pk_add_f32 v[94:95], v[98:99], v[94:95]
	v_lshl_add_u64 v[96:97], v[96:97], 0, v[120:121]
	global_store_dwordx4 v[96:97], v[92:95], off nt
	global_store_dwordx4 v[96:97], v[88:91], off offset:16 nt
	s_nop 1
	v_lshlrev_b32_e32 v88, 16, v222
	v_and_b32_e32 v89, 0xffff0000, v222
	v_pk_add_f32 v[84:85], v[84:85], v[88:89]
	v_lshlrev_b32_e32 v88, 16, v223
	v_and_b32_e32 v89, 0xffff0000, v223
	v_pk_add_f32 v[86:87], v[86:87], v[88:89]
	v_lshlrev_b32_e32 v88, 16, v224
	v_and_b32_e32 v89, 0xffff0000, v224
	v_pk_add_f32 v[76:77], v[76:77], v[88:89]
	v_lshlrev_b32_e32 v88, 16, v225
	v_and_b32_e32 v89, 0xffff0000, v225
	v_pk_add_f32 v[78:79], v[78:79], v[88:89]
	global_store_dwordx4 v[96:97], v[84:87], off offset:512 nt
	global_store_dwordx4 v[96:97], v[76:79], off offset:528 nt
	s_nop 1
	v_lshlrev_b32_e32 v76, 16, v164
	v_and_b32_e32 v77, 0xffff0000, v164
	v_pk_add_f32 v[76:77], v[80:81], v[76:77]
	v_lshlrev_b32_e32 v80, 16, v166
	v_and_b32_e32 v81, 0xffff0000, v166
	v_pk_add_f32 v[72:73], v[72:73], v[80:81]
	v_lshlrev_b32_e32 v80, 16, v167
	v_and_b32_e32 v81, 0xffff0000, v167
	v_pk_add_f32 v[74:75], v[74:75], v[80:81]
	v_lshlrev_b64 v[80:81], 12, v[196:197]
	v_lshlrev_b32_e32 v78, 16, v165
	v_and_b32_e32 v79, 0xffff0000, v165
	v_lshl_add_u64 v[80:81], s[76:77], 0, v[80:81]
	v_pk_add_f32 v[78:79], v[82:83], v[78:79]
	v_lshl_add_u64 v[80:81], v[80:81], 0, v[120:121]
	global_store_dwordx4 v[80:81], v[76:79], off nt
	global_store_dwordx4 v[80:81], v[72:75], off offset:16 nt
	s_nop 1
	v_lshlrev_b32_e32 v72, 16, v160
	v_and_b32_e32 v73, 0xffff0000, v160
	v_pk_add_f32 v[68:69], v[68:69], v[72:73]
	v_lshlrev_b32_e32 v72, 16, v161
	v_and_b32_e32 v73, 0xffff0000, v161
	v_pk_add_f32 v[70:71], v[70:71], v[72:73]
	v_lshlrev_b32_e32 v72, 16, v162
	v_and_b32_e32 v73, 0xffff0000, v162
	v_pk_add_f32 v[64:65], v[64:65], v[72:73]
	v_lshlrev_b32_e32 v72, 16, v163
	v_and_b32_e32 v73, 0xffff0000, v163
	v_pk_add_f32 v[66:67], v[66:67], v[72:73]
	global_store_dwordx4 v[80:81], v[68:71], off offset:512 nt
	global_store_dwordx4 v[80:81], v[64:67], off offset:528 nt
	s_nop 1
	v_lshlrev_b32_e32 v64, 16, v156
	v_and_b32_e32 v65, 0xffff0000, v156
	v_pk_add_f32 v[60:61], v[60:61], v[64:65]
	v_lshlrev_b32_e32 v64, 16, v157
	v_and_b32_e32 v65, 0xffff0000, v157
	v_pk_add_f32 v[62:63], v[62:63], v[64:65]
	v_lshlrev_b32_e32 v64, 16, v158
	v_and_b32_e32 v65, 0xffff0000, v158
	v_pk_add_f32 v[56:57], v[56:57], v[64:65]
	v_lshlrev_b32_e32 v64, 16, v159
	v_and_b32_e32 v65, 0xffff0000, v159
	v_pk_add_f32 v[58:59], v[58:59], v[64:65]
	v_lshlrev_b64 v[64:65], 12, v[194:195]
	v_lshl_add_u64 v[64:65], s[76:77], 0, v[64:65]
	v_lshl_add_u64 v[64:65], v[64:65], 0, v[120:121]
	global_store_dwordx4 v[64:65], v[60:63], off nt
	global_store_dwordx4 v[64:65], v[56:59], off offset:16 nt
	s_nop 1
	v_lshlrev_b32_e32 v56, 16, v152
	v_and_b32_e32 v57, 0xffff0000, v152
	v_pk_add_f32 v[52:53], v[52:53], v[56:57]
	v_lshlrev_b32_e32 v56, 16, v153
	v_and_b32_e32 v57, 0xffff0000, v153
	v_pk_add_f32 v[54:55], v[54:55], v[56:57]
	v_lshlrev_b32_e32 v56, 16, v154
	v_and_b32_e32 v57, 0xffff0000, v154
	v_pk_add_f32 v[44:45], v[44:45], v[56:57]
	v_lshlrev_b32_e32 v56, 16, v155
	v_and_b32_e32 v57, 0xffff0000, v155
	v_pk_add_f32 v[46:47], v[46:47], v[56:57]
	global_store_dwordx4 v[64:65], v[52:55], off offset:512 nt
	global_store_dwordx4 v[64:65], v[44:47], off offset:528 nt
	s_nop 1
	v_lshlrev_b32_e32 v44, 16, v148
	v_and_b32_e32 v45, 0xffff0000, v148
	v_pk_add_f32 v[44:45], v[48:49], v[44:45]
	v_lshlrev_b32_e32 v48, 16, v150
	v_and_b32_e32 v49, 0xffff0000, v150
	v_pk_add_f32 v[40:41], v[40:41], v[48:49]
;     __device__ __forceinline__ void operator()(const f32x4 (&acc)[2][2][4][2], const pg8::Unit& u, int wr, int wc, int fr, int fq) const {
;     ...
;                 for (int bj = 0; bj < 2; ++bj) {
;                     const size_t off = (size_t)row * DM + u.pn * 256 + 128 * bj + 32 * wc + 8 * fq;
;                     const u32x4 w = xr[ai][m][bj];
;                     f32x4 ya = acc[ai][bj][m][0], yb = acc[ai][bj][m][1];
;                     ya.x += __uint_as_float(w.x << 16); ya.y += __uint_as_float(w.x & 0xffff0000u); ya.z += __uint_as_float(w.y << 16); ya.w += __uint_as_float(w.y & 0xffff0000u);
;                     yb.x += __uint_as_float(w.z << 16); yb.y += __uint_as_float(w.z & 0xffff0000u); yb.z += __uint_as_float(w.w << 16); yb.w += __uint_as_float(w.w & 0xffff0000u);
;                     *(f32x4*)(out + off) = ya; *(f32x4*)(out + off + 4) = yb;
;                 }
;             }
	v_lshlrev_b32_e32 v48, 16, v151
	v_and_b32_e32 v49, 0xffff0000, v151
	v_pk_add_f32 v[42:43], v[42:43], v[48:49]
	v_lshlrev_b64 v[48:49], 12, v[192:193]
	v_lshlrev_b32_e32 v46, 16, v149
	v_and_b32_e32 v47, 0xffff0000, v149
	v_lshl_add_u64 v[48:49], s[76:77], 0, v[48:49]
	v_pk_add_f32 v[46:47], v[50:51], v[46:47]
	v_lshl_add_u64 v[48:49], v[48:49], 0, v[120:121]
	global_store_dwordx4 v[48:49], v[44:47], off nt
	global_store_dwordx4 v[48:49], v[40:43], off offset:16 nt
	s_nop 1
	v_lshlrev_b32_e32 v40, 16, v144
	v_and_b32_e32 v41, 0xffff0000, v144
	v_pk_add_f32 v[36:37], v[36:37], v[40:41]
	v_lshlrev_b32_e32 v40, 16, v145
	v_and_b32_e32 v41, 0xffff0000, v145
	v_pk_add_f32 v[38:39], v[38:39], v[40:41]
	v_lshlrev_b32_e32 v40, 16, v146
	v_and_b32_e32 v41, 0xffff0000, v146
	v_pk_add_f32 v[28:29], v[28:29], v[40:41]
	v_lshlrev_b32_e32 v40, 16, v147
	v_and_b32_e32 v41, 0xffff0000, v147
	v_pk_add_f32 v[30:31], v[30:31], v[40:41]
	global_store_dwordx4 v[48:49], v[36:39], off offset:512 nt
	global_store_dwordx4 v[48:49], v[28:31], off offset:528 nt
	s_nop 1
	v_lshlrev_b32_e32 v28, 16, v140
	v_and_b32_e32 v29, 0xffff0000, v140
	v_pk_add_f32 v[28:29], v[32:33], v[28:29]
	v_lshlrev_b32_e32 v32, 16, v142
	v_and_b32_e32 v33, 0xffff0000, v142
	v_pk_add_f32 v[24:25], v[24:25], v[32:33]
	v_lshlrev_b32_e32 v32, 16, v143
	v_and_b32_e32 v33, 0xffff0000, v143
	v_pk_add_f32 v[26:27], v[26:27], v[32:33]
	v_lshlrev_b64 v[32:33], 12, v[190:191]
	v_lshlrev_b32_e32 v30, 16, v141
	v_and_b32_e32 v31, 0xffff0000, v141
	v_lshl_add_u64 v[32:33], s[76:77], 0, v[32:33]
	v_pk_add_f32 v[30:31], v[34:35], v[30:31]
	v_lshl_add_u64 v[32:33], v[32:33], 0, v[120:121]
	global_store_dwordx4 v[32:33], v[28:31], off nt
	global_store_dwordx4 v[32:33], v[24:27], off offset:16 nt
	s_nop 1
	v_lshlrev_b32_e32 v24, 16, v136
	v_and_b32_e32 v25, 0xffff0000, v136
	v_pk_add_f32 v[20:21], v[20:21], v[24:25]
	v_lshlrev_b32_e32 v24, 16, v137
	v_and_b32_e32 v25, 0xffff0000, v137
	v_pk_add_f32 v[22:23], v[22:23], v[24:25]
	v_lshlrev_b32_e32 v24, 16, v138
	v_and_b32_e32 v25, 0xffff0000, v138
	v_pk_add_f32 v[12:13], v[12:13], v[24:25]
	v_lshlrev_b32_e32 v24, 16, v139
	v_and_b32_e32 v25, 0xffff0000, v139
	v_pk_add_f32 v[14:15], v[14:15], v[24:25]
	global_store_dwordx4 v[32:33], v[20:23], off offset:512 nt
	global_store_dwordx4 v[32:33], v[12:15], off offset:528 nt
	s_nop 1
	v_lshlrev_b32_e32 v12, 16, v132
	v_and_b32_e32 v13, 0xffff0000, v132
	v_pk_add_f32 v[12:13], v[16:17], v[12:13]
	v_lshlrev_b32_e32 v16, 16, v134
	v_and_b32_e32 v17, 0xffff0000, v134
	v_pk_add_f32 v[8:9], v[8:9], v[16:17]
	v_lshlrev_b32_e32 v16, 16, v135
	v_and_b32_e32 v17, 0xffff0000, v135
	v_pk_add_f32 v[10:11], v[10:11], v[16:17]
	v_lshlrev_b64 v[16:17], 12, v[188:189]
	v_lshlrev_b32_e32 v14, 16, v133
	v_and_b32_e32 v15, 0xffff0000, v133
	v_lshl_add_u64 v[16:17], s[76:77], 0, v[16:17]
	v_pk_add_f32 v[14:15], v[18:19], v[14:15]
	v_lshl_add_u64 v[16:17], v[16:17], 0, v[120:121]
	global_store_dwordx4 v[16:17], v[12:15], off nt
	global_store_dwordx4 v[16:17], v[8:11], off offset:16 nt
	s_nop 1
	v_lshlrev_b32_e32 v8, 16, v128
	v_and_b32_e32 v9, 0xffff0000, v128
	v_pk_add_f32 v[4:5], v[4:5], v[8:9]
	v_lshlrev_b32_e32 v8, 16, v129
	v_and_b32_e32 v9, 0xffff0000, v129
	v_pk_add_f32 v[6:7], v[6:7], v[8:9]
	v_lshlrev_b32_e32 v8, 16, v130
	v_and_b32_e32 v9, 0xffff0000, v130
	v_pk_add_f32 v[0:1], v[0:1], v[8:9]
	v_lshlrev_b32_e32 v8, 16, v131
	v_and_b32_e32 v9, 0xffff0000, v131
	v_pk_add_f32 v[2:3], v[2:3], v[8:9]
	global_store_dwordx4 v[16:17], v[4:7], off offset:512 nt
	global_store_dwordx4 v[16:17], v[0:3], off offset:528 nt
	s_cbranch_vccnz .LBB0_1053
	s_andn2_b64 vcc, exec, s[2:3]
	s_cbranch_vccnz .LBB0_1052
	s_barrier
	s_branch .LBB0_1052
